# FoX dynamic queue: next ticket requested at the unit epilogue start and collected with a counted wait that leaves the four output stores outstanding (on top of the MLA next-unit prefetch)
# baseline (speedup 1.0000x reference)
; DI void phase3(const Params& p, unsigned char* smem, int tid, int cidx) {
;     ...
;     for (;;) {
;         if (tid == 0) sh[0] = (int)atomicAdd(ctr, 1u);
;         __syncthreads();
;         const int u = sh[0];
;         __syncthreads();
;         if (u >= nun) break;
.Lql_have:
	s_waitcnt vmcnt(4)
	v_mov_b32_e32 v2, v246
	s_mov_b32 s98, 0
	s_or_b64 exec, exec, s[20:21]
	s_branch .Lql_after
.Lql_done:
.LBB0_774:
	s_or_b64 exec, exec, s[20:21]
	s_waitcnt vmcnt(0)
.Lql_after:
	v_readfirstlane_b32 s2, v2
	s_nop 1
	v_add_u32_e32 v1, s2, v1
	ds_write_b32 v0, v1
